# la_lb2: the same loop-invariant log-base loads removed from the la_range_state chunk loop
# speedup vs baseline: 1.0095x; 1.0019x over previous
.LBB0_294:
	s_cmp_lg_u32 s16, 15
	s_cselect_b64 s[20:21], -1, 0
	s_cmp_lg_u64 s[20:21], 0
	s_addc_u32 s25, s10, s16
	v_cndmask_b32_e64 v32, 0, 1, s[20:21]
	s_add_u32 s20, s10, s16
	v_mov_b32_e32 v33, s24
	s_addc_u32 s21, s11, s17
	v_lshl_add_u64 v[32:33], s[20:21], 0, v[32:33]
	v_lshlrev_b64 v[32:33], 16, v[32:33]
	v_lshl_add_u64 v[32:33], s[12:13], 0, v[32:33]
	v_lshl_add_u64 v[40:41], v[32:33], 0, v[48:49]
	v_add_co_u32_e32 v32, vcc, s3, v40
	s_and_b32 s20, s25, 0x180
	s_nop 0
	v_addc_co_u32_e32 v33, vcc, 0, v41, vcc
	v_add_co_u32_e32 v36, vcc, s19, v40
	v_or_b32_e32 v52, s20, v102
	s_nop 0
	v_addc_co_u32_e32 v37, vcc, 0, v41, vcc
	v_add_co_u32_e32 v42, vcc, s22, v40
	v_lshlrev_b32_e32 v52, 2, v52
	s_nop 0
	v_addc_co_u32_e32 v43, vcc, 0, v41, vcc
	v_add_co_u32_e32 v44, vcc, s23, v40
	s_waitcnt lgkmcnt(0)
	global_load_dwordx4 v[32:35], v[32:33], off
	s_nop 0
	global_load_dwordx4 v[36:39], v[36:37], off
	v_addc_co_u32_e32 v45, vcc, 0, v41, vcc
	global_load_dwordx4 v[40:43], v[42:43], off
	s_nop 0
	global_load_dwordx4 v[44:47], v[44:45], off
	s_nop 0
	ds_read_u16 v52, v113
	ds_read_u16 v53, v113 offset:288
	ds_read_u16 v54, v113 offset:576
	ds_read_u16 v55, v113 offset:864
	ds_read_u16 v56, v113 offset:1152
	ds_read_u16 v57, v113 offset:1440
	ds_read_u16 v58, v113 offset:1728
	ds_read_u16 v59, v113 offset:2016
	ds_read_u16 v60, v113 offset:2304
	ds_read_u16 v61, v113 offset:2592
	ds_read_u16 v62, v113 offset:2880
	ds_read_u16 v63, v113 offset:3168
	ds_read_u16 v64, v113 offset:3456
	ds_read_u16 v65, v113 offset:3744
	ds_read_u16 v66, v113 offset:4032
	ds_read_u16 v67, v113 offset:4320
	ds_read_u16 v126, v113 offset:20480
	ds_read_u16 v132, v113 offset:20768
	ds_read_u16 v127, v113 offset:21056
	ds_read_u16 v133, v113 offset:21344
	ds_read_u16 v130, v113 offset:21632
	ds_read_u16 v134, v113 offset:21920
	ds_read_u16 v131, v113 offset:22208
	ds_read_u16 v135, v113 offset:22496
	ds_read_u16 v118, v113 offset:22784
	ds_read_u16 v122, v113 offset:23072
	ds_read_u16 v119, v113 offset:23360
	ds_read_u16 v123, v113 offset:23648
	ds_read_u16 v120, v113 offset:23936
	ds_read_u16 v124, v113 offset:24224
	ds_read_u16 v121, v113 offset:24512
	ds_read_u16 v125, v113 offset:24800
	s_waitcnt lgkmcnt(0)
	s_barrier
	s_and_b64 vcc, exec, s[14:15]
	s_waitcnt lgkmcnt(14)
	v_lshlrev_b32_e32 v69, 16, v67
	v_lshlrev_b32_e32 v68, 16, v52
	v_lshlrev_b32_e32 v99, 16, v53
	v_lshlrev_b32_e32 v98, 16, v54
	v_lshlrev_b32_e32 v93, 16, v55
	v_lshlrev_b32_e32 v92, 16, v56
	v_lshlrev_b32_e32 v91, 16, v57
	v_lshlrev_b32_e32 v90, 16, v58
	v_lshlrev_b32_e32 v87, 16, v59
	v_lshlrev_b32_e32 v86, 16, v60
	v_lshlrev_b32_e32 v81, 16, v61
	v_lshlrev_b32_e32 v80, 16, v62
	v_lshlrev_b32_e32 v77, 16, v63
	v_lshlrev_b32_e32 v76, 16, v64
	v_lshlrev_b32_e32 v75, 16, v65
	v_lshlrev_b32_e32 v74, 16, v66
	s_mov_b64 s[20:21], -1
	s_cbranch_vccz .LBB0_296
	v_pk_mul_f32 v[52:53], v[98:99], s[18:19] op_sel_hi:[1,0]
	v_pk_mul_f32 v[54:55], v[92:93], s[18:19] op_sel_hi:[1,0]
	v_pk_mul_f32 v[58:59], v[90:91], s[18:19] op_sel_hi:[1,0]
	v_pk_mul_f32 v[64:65], v[86:87], s[18:19] op_sel_hi:[1,0]
	v_pk_mul_f32 v[72:73], v[80:81], s[18:19] op_sel_hi:[1,0]
	v_pk_mul_f32 v[82:83], v[76:77], s[18:19] op_sel_hi:[1,0]
	v_pk_mul_f32 v[88:89], v[74:75], s[18:19] op_sel_hi:[1,0]
	v_pk_mul_f32 v[62:63], v[68:69], s[18:19] op_sel_hi:[1,0]
	s_mov_b64 s[20:21], 0

.LBB0_298:
	v_pk_mul_f32 v[80:81], v[96:97], v[96:97] op_sel:[1,0] op_sel_hi:[0,1]
	v_pk_mul_f32 v[86:87], v[80:81], v[94:95]
	v_pk_mul_f32 v[68:69], v[96:97], v[88:89] op_sel:[1,0] op_sel_hi:[0,1]
	v_mov_b32_e32 v96, v86
	v_mov_b32_e32 v97, v80
	v_mov_b32_e32 v88, v82
	v_pk_mul_f32 v[86:87], v[86:87], v[94:95] op_sel:[0,1] op_sel_hi:[1,0]
	v_pk_mul_f32 v[80:81], v[96:97], v[88:89]
	v_pk_mul_f32 v[88:89], v[86:87], v[84:85]
	v_mov_b32_e32 v95, v86
	v_pk_mul_f32 v[84:85], v[88:89], v[84:85] op_sel:[0,1] op_sel_hi:[1,0]
	v_lshlrev_b32_e32 v69, 16, v132
	v_pk_mul_f32 v[86:87], v[84:85], v[78:79]
	v_mov_b32_e32 v89, v84
	v_pk_mul_f32 v[78:79], v[86:87], v[78:79] op_sel:[0,1] op_sel_hi:[1,0]
	v_or_b32_sdwa v74, v69, v126 dst_sel:DWORD dst_unused:UNUSED_PAD src0_sel:DWORD src1_sel:WORD_0
	v_pk_mul_f32 v[84:85], v[78:79], v[70:71]
	v_mov_b32_e32 v87, v78
	v_pk_mul_f32 v[70:71], v[84:85], v[70:71] op_sel:[0,1] op_sel_hi:[1,0]
	s_waitcnt lgkmcnt(12)
	v_lshlrev_b32_e32 v69, 16, v133
	v_pk_mul_f32 v[78:79], v[70:71], v[66:67]
	v_mov_b32_e32 v94, v88
	v_mov_b32_e32 v82, v72
	v_mov_b32_e32 v88, v86
	v_mov_b32_e32 v72, v64
	v_mov_b32_e32 v86, v84
	v_mov_b32_e32 v64, v58
	v_mov_b32_e32 v84, v78
	v_mov_b32_e32 v85, v70
	v_mov_b32_e32 v58, v54
	v_or_b32_sdwa v75, v69, v127 dst_sel:DWORD dst_unused:UNUSED_PAD src0_sel:DWORD src1_sel:WORD_0
	s_waitcnt lgkmcnt(10)
	v_lshlrev_b32_e32 v69, 16, v134
	v_pk_mul_f32 v[70:71], v[84:85], v[58:59]
	v_pk_mul_f32 v[58:59], v[78:79], v[66:67] op_sel:[0,1] op_sel_hi:[1,0]
	v_or_b32_sdwa v76, v69, v130 dst_sel:DWORD dst_unused:UNUSED_PAD src0_sel:DWORD src1_sel:WORD_0
	s_waitcnt lgkmcnt(8)
	v_lshlrev_b32_e32 v69, 16, v135
	v_pk_mul_f32 v[66:67], v[58:59], v[60:61]
	v_or_b32_sdwa v77, v69, v131 dst_sel:DWORD dst_unused:UNUSED_PAD src0_sel:DWORD src1_sel:WORD_0
	s_waitcnt lgkmcnt(6)
	v_lshlrev_b32_e32 v69, 16, v122
	v_mov_b32_e32 v79, v58
	v_pk_mul_f32 v[58:59], v[66:67], v[60:61] op_sel:[0,1] op_sel_hi:[1,0]
	v_or_b32_sdwa v90, v69, v118 dst_sel:DWORD dst_unused:UNUSED_PAD src0_sel:DWORD src1_sel:WORD_0
	s_waitcnt lgkmcnt(4)
	v_lshlrev_b32_e32 v69, 16, v123
	v_pk_mul_f32 v[60:61], v[58:59], v[56:57]
	v_or_b32_sdwa v91, v69, v119 dst_sel:DWORD dst_unused:UNUSED_PAD src0_sel:DWORD src1_sel:WORD_0
	s_waitcnt lgkmcnt(2)
	v_lshlrev_b32_e32 v69, 16, v124
	v_mov_b32_e32 v54, v52
	v_mul_f32_e32 v52, v60, v57
	v_or_b32_sdwa v92, v69, v120 dst_sel:DWORD dst_unused:UNUSED_PAD src0_sel:DWORD src1_sel:WORD_0
	s_waitcnt lgkmcnt(0)
	v_lshlrev_b32_e32 v69, 16, v125
	ds_write_b32 v104, v52 offset:40960
	v_add_u32_e32 v52, v106, v105
	v_or_b32_sdwa v93, v69, v121 dst_sel:DWORD dst_unused:UNUSED_PAD src0_sel:DWORD src1_sel:WORD_0
	ds_write_b128 v52, v[74:77] offset:20480
	ds_write_b128 v52, v[90:93] offset:20496
	v_mov_b32_e32 v78, v66
	s_waitcnt lgkmcnt(0)
	s_barrier
	v_pk_mul_f32 v[78:79], v[78:79], v[54:55]
	ds_read2st64_b32 v[54:55], v109 offset0:160 offset1:162
	ds_read2st64_b32 v[56:57], v109 offset0:164 offset1:166
	v_mov_b32_e32 v61, v58
	v_mov_b32_e32 v52, v62
	v_pk_mul_f32 v[52:53], v[60:61], v[52:53]
	s_waitcnt lgkmcnt(1)
	v_cndmask_b32_e64 v58, 1.0, v55, s[4:5]
	s_waitcnt lgkmcnt(0)
	v_mul_f32_e32 v58, v58, v56
	v_cndmask_b32_e64 v58, 1.0, v58, s[6:7]
	v_mul_f32_e32 v58, v57, v58
	v_cndmask_b32_e64 v62, 1.0, v58, s[8:9]
	v_pk_mul_f32 v[52:53], v[52:53], v[62:63] op_sel_hi:[1,0]
	v_pk_mul_f32 v[64:65], v[86:87], v[64:65]
	v_cvt_pk_bf16_f32 v58, v52, v53
	v_pk_mul_f32 v[52:53], v[78:79], v[62:63] op_sel_hi:[1,0]
	v_pk_mul_f32 v[72:73], v[88:89], v[72:73]
	v_cvt_pk_bf16_f32 v59, v52, v53
	v_pk_mul_f32 v[52:53], v[70:71], v[62:63] op_sel_hi:[1,0]
	v_pk_mul_f32 v[82:83], v[94:95], v[82:83]
	v_cvt_pk_bf16_f32 v60, v52, v53
	v_pk_mul_f32 v[52:53], v[64:65], v[62:63] op_sel_hi:[1,0]
	v_mov_b32_e32 v69, v63
	v_cvt_pk_bf16_f32 v61, v52, v53
	v_pk_mul_f32 v[52:53], v[72:73], v[62:63] op_sel_hi:[1,0]
	s_nop 0
	v_cvt_pk_bf16_f32 v64, v52, v53
	v_pk_mul_f32 v[52:53], v[82:83], v[62:63] op_sel_hi:[1,0]
	s_nop 0
	v_cvt_pk_bf16_f32 v65, v52, v53
	v_pk_mul_f32 v[52:53], v[80:81], v[62:63] op_sel_hi:[1,0]
	s_nop 0
	v_cvt_pk_bf16_f32 v66, v52, v53
	v_pk_mul_f32 v[52:53], v[68:69], v[62:63] op_sel_hi:[1,0]
	s_nop 0
	v_cvt_pk_bf16_f32 v67, v52, v53
	v_add_u32_e32 v52, v110, v105
	ds_write_b128 v52, v[58:61]
	ds_write_b128 v52, v[64:67] offset:16
	s_and_saveexec_b64 s[20:21], s[4:5]
	v_mul_f32_e32 v52, v54, v55
	v_mul_f32_e32 v52, v52, v56
	v_mul_f32_e32 v52, v52, v57
	v_mul_f32_e32 v101, v101, v52
	ds_write_b32 v114, v52 offset:43008
	s_or_b64 exec, exec, s[20:21]
	s_waitcnt lgkmcnt(0)
	s_barrier
	ds_read_b128 v[52:55], v111 offset:43008
	ds_read_b128 v[56:59], v111 offset:43072
	ds_read_b128 v[62:65], v115
	s_add_u32 s16, s16, 1
	s_addc_u32 s17, s17, 0
	s_waitcnt lgkmcnt(2)
	v_pk_mul_f32 v[30:31], v[30:31], v[54:55]
	v_pk_mul_f32 v[28:29], v[28:29], v[52:53]
	ds_read_b128 v[52:55], v111 offset:43136
	s_waitcnt lgkmcnt(2)
	v_pk_mul_f32 v[26:27], v[26:27], v[58:59]
	ds_read_b128 v[58:61], v111 offset:43200
	v_pk_mul_f32 v[24:25], v[24:25], v[56:57]
	s_cmp_eq_u32 s16, 16
	s_waitcnt lgkmcnt(1)
	v_pk_mul_f32 v[22:23], v[22:23], v[54:55]
	v_pk_mul_f32 v[20:21], v[20:21], v[52:53]
	ds_read_b128 v[52:55], v112 offset:20480
	s_waitcnt lgkmcnt(1)
	v_pk_mul_f32 v[16:17], v[16:17], v[58:59]
	ds_read_b128 v[56:59], v115 offset:2560
	ds_read_b128 v[66:69], v112 offset:20544
	ds_read_b128 v[70:73], v115 offset:64
	v_pk_mul_f32 v[18:19], v[18:19], v[60:61]
	s_waitcnt lgkmcnt(3)
	v_mfma_f32_16x16x32_bf16 v[28:31], v[62:65], v[52:55], v[28:31]
	ds_read_b128 v[60:63], v115 offset:5120
	ds_read_b128 v[74:77], v111 offset:43264
	ds_read_b128 v[78:81], v111 offset:43328
	ds_read_b128 v[82:85], v115 offset:7680
	ds_read_b128 v[86:89], v115 offset:2624
	s_waitcnt lgkmcnt(3)
	v_pk_mul_f32 v[14:15], v[14:15], v[76:77]
	v_mfma_f32_16x16x32_bf16 v[24:27], v[56:59], v[52:55], v[24:27]
	ds_read_b128 v[56:59], v115 offset:10240
	ds_read_b128 v[90:93], v115 offset:5184
	v_pk_mul_f32 v[12:13], v[12:13], v[74:75]
	ds_read_b128 v[74:77], v115 offset:12800
	v_mfma_f32_16x16x32_bf16 v[20:23], v[60:63], v[52:55], v[20:23]
	s_waitcnt lgkmcnt(5)
	v_pk_mul_f32 v[10:11], v[10:11], v[80:81]
	ds_read_b128 v[60:63], v115 offset:7744
	v_pk_mul_f32 v[8:9], v[8:9], v[78:79]
	s_waitcnt lgkmcnt(5)
	v_mfma_f32_16x16x32_bf16 v[16:19], v[82:85], v[52:55], v[16:19]
	ds_read_b128 v[78:81], v115 offset:10304
	s_waitcnt lgkmcnt(4)
	v_mfma_f32_16x16x32_bf16 v[12:15], v[56:59], v[52:55], v[12:15]
	ds_read_b128 v[56:59], v115 offset:15360
	ds_read_b128 v[82:85], v111 offset:43392
	ds_read_b128 v[94:97], v111 offset:43456
	ds_read_b128 v[118:121], v115 offset:17920
	ds_read_b128 v[122:125], v115 offset:12864
	s_waitcnt lgkmcnt(3)
	v_pk_mul_f32 v[2:3], v[2:3], v[84:85]
	v_pk_mul_f32 v[0:1], v[0:1], v[82:83]
	v_mfma_f32_16x16x32_bf16 v[8:11], v[74:77], v[52:55], v[8:11]
	ds_read_b128 v[74:77], v115 offset:15424
	s_waitcnt lgkmcnt(3)
	v_pk_mul_f32 v[6:7], v[6:7], v[96:97]
	v_pk_mul_f32 v[4:5], v[4:5], v[94:95]
	v_mfma_f32_16x16x32_bf16 v[0:3], v[56:59], v[52:55], v[0:3]
	ds_read_b128 v[56:59], v115 offset:17984
	s_waitcnt lgkmcnt(0)
	s_barrier
	s_waitcnt lgkmcnt(3)
	v_mfma_f32_16x16x32_bf16 v[4:7], v[118:121], v[52:55], v[4:7]
	s_waitcnt vmcnt(3)
	ds_write_b128 v107, v[32:35]
	s_waitcnt vmcnt(2)
	ds_write_b128 v107, v[36:39] offset:20480
	s_waitcnt vmcnt(1)
	ds_write_b128 v108, v[40:43]
	s_waitcnt vmcnt(0)
	ds_write_b128 v108, v[44:47] offset:20480
	s_waitcnt lgkmcnt(0)
	v_mfma_f32_16x16x32_bf16 v[28:31], v[70:73], v[66:69], v[28:31]
	s_barrier
	v_mfma_f32_16x16x32_bf16 v[24:27], v[86:89], v[66:69], v[24:27]
	v_mfma_f32_16x16x32_bf16 v[20:23], v[90:93], v[66:69], v[20:23]
	v_mfma_f32_16x16x32_bf16 v[16:19], v[60:63], v[66:69], v[16:19]
	v_mfma_f32_16x16x32_bf16 v[12:15], v[78:81], v[66:69], v[12:15]
	s_waitcnt lgkmcnt(6)
	v_mfma_f32_16x16x32_bf16 v[8:11], v[122:125], v[66:69], v[8:11]
	s_waitcnt lgkmcnt(5)
	v_mfma_f32_16x16x32_bf16 v[0:3], v[74:77], v[66:69], v[0:3]
	s_waitcnt lgkmcnt(4)
	v_mfma_f32_16x16x32_bf16 v[4:7], v[56:59], v[66:69], v[4:7]
	s_cbranch_scc1 .LBB0_302
	s_waitcnt vmcnt(0)
	s_branch .LBB0_294
